# scan chunk body hand-scheduled: LDS operands requested one pair ahead (two register banks)
# speedup vs baseline: 1.0171x; 1.0121x over previous
.LBB0_1092:
	s_mov_b64 s[92:93], -1
	s_and_b64 vcc, exec, s[88:89]
	s_cbranch_vccz .LBB0_1098
	s_bitcmp1_b32 s9, 0
	s_cselect_b32 s7, 0xb200, 0
	s_add_i32 s26, s7, 0
	s_mov_b64 s[82:83], s[96:97]
	s_mov_b32 s84, s80
	v_lshl_add_u32 v174, v102, 2, s26
	v_mov_b32_e32 v175, s26
	v_add_u32_e32 v163, s26, v160
	v_mov_b64_e32 v[144:145], v[140:141]
	v_mov_b64_e32 v[146:147], v[142:143]
	v_mov_b32_e32 v162, v111
	ds_read_b128 v[0:3], v174 offset:0
	ds_read_b128 v[4:7], v174 offset:256
	ds_read_b128 v[8:11], v174 offset:512
	ds_read_b128 v[12:15], v174 offset:768
	ds_read_b128 v[16:19], v174 offset:1024
	ds_read_b128 v[20:23], v174 offset:1280
	ds_read_b128 v[24:27], v174 offset:1536
	ds_read_b128 v[28:31], v174 offset:1792
	ds_read_b128 v[32:35], v174 offset:2048
	ds_read_b128 v[36:39], v175 offset:2816
	ds_read_b32 v40, v163 offset:2304
	ds_read_b32 v41, v163 offset:2560
	s_waitcnt lgkmcnt(0)
	v_pk_mul_f32 v[96:97], v[144:145], v[50:51]
	v_pk_mul_f32 v[98:99], v[144:145], v[0:1]
	v_pk_mul_f32 v[100:101], v[144:145], v[4:5]
	v_pk_mul_f32 v[172:173], v[144:145], v[8:9]
	v_pk_fma_f32 v[96:97], v[146:147], v[52:53], v[96:97]
	v_pk_fma_f32 v[98:99], v[146:147], v[2:3], v[98:99]
	v_pk_fma_f32 v[100:101], v[146:147], v[6:7], v[100:101]
	v_pk_fma_f32 v[172:173], v[146:147], v[10:11], v[172:173]
	ds_read_b128 v[54:57], v174 offset:2848
	ds_read_b128 v[58:61], v174 offset:3104
	ds_read_b128 v[62:65], v174 offset:3360
	ds_read_b128 v[66:69], v174 offset:3616
	ds_read_b128 v[70:73], v174 offset:3872
	ds_read_b128 v[74:77], v174 offset:4128
	ds_read_b128 v[78:81], v174 offset:4384
	ds_read_b128 v[82:85], v174 offset:4640
	ds_read_b128 v[86:89], v174 offset:4896
	ds_read_b128 v[90:93], v175 offset:5664
	ds_read_b32 v94, v163 offset:5152
	ds_read_b32 v95, v163 offset:5408
	v_pk_mul_f32 v[148:149], v[24:25], v[40:41] op_sel_hi:[1,0]
	v_pk_mul_f32 v[150:151], v[26:27], v[40:41] op_sel_hi:[1,0]
	v_add_f32_e32 v168, v96, v97
	v_add_f32_e32 v166, v98, v99
	v_add_f32_e32 v169, v100, v101
	v_add_f32_e32 v170, v172, v173
	v_pk_fma_f32 v[148:149], v[32:33], v[40:41], v[148:149] op_sel:[0,1,0] op_sel_hi:[1,1,1]
	v_pk_fma_f32 v[150:151], v[34:35], v[40:41], v[150:151] op_sel:[0,1,0] op_sel_hi:[1,1,1]
	v_add_f32_dpp v168, v168, v168 row_mirror row_mask:0xf bank_mask:0xf bound_ctrl:1
	v_add_f32_dpp v166, v166, v166 row_mirror row_mask:0xf bank_mask:0xf bound_ctrl:1
	v_add_f32_dpp v169, v169, v169 row_mirror row_mask:0xf bank_mask:0xf bound_ctrl:1
	v_add_f32_dpp v170, v170, v170 row_mirror row_mask:0xf bank_mask:0xf bound_ctrl:1
	v_add_f32_dpp v168, v168, v168 row_half_mirror row_mask:0xf bank_mask:0xf bound_ctrl:1
	v_add_f32_dpp v166, v166, v166 row_half_mirror row_mask:0xf bank_mask:0xf bound_ctrl:1
	v_add_f32_dpp v169, v169, v169 row_half_mirror row_mask:0xf bank_mask:0xf bound_ctrl:1
	v_add_f32_dpp v170, v170, v170 row_half_mirror row_mask:0xf bank_mask:0xf bound_ctrl:1
	v_add_f32_dpp v168, v168, v168 quad_perm:[1,0,3,2] row_mask:0xf bank_mask:0xf bound_ctrl:1
	v_add_f32_dpp v166, v166, v166 quad_perm:[1,0,3,2] row_mask:0xf bank_mask:0xf bound_ctrl:1
	v_add_f32_dpp v169, v169, v169 quad_perm:[1,0,3,2] row_mask:0xf bank_mask:0xf bound_ctrl:1
	v_add_f32_dpp v170, v170, v170 quad_perm:[1,0,3,2] row_mask:0xf bank_mask:0xf bound_ctrl:1
	v_add_f32_dpp v168, v168, v168 quad_perm:[2,3,0,1] row_mask:0xf bank_mask:0xf bound_ctrl:1
	v_add_f32_dpp v166, v166, v166 quad_perm:[2,3,0,1] row_mask:0xf bank_mask:0xf bound_ctrl:1
	v_add_f32_dpp v169, v169, v169 quad_perm:[2,3,0,1] row_mask:0xf bank_mask:0xf bound_ctrl:1
	v_add_f32_dpp v170, v170, v170 quad_perm:[2,3,0,1] row_mask:0xf bank_mask:0xf bound_ctrl:1
	v_fma_f32 v164, v40, v37, v169
	v_fma_f32 v171, v40, v39, v170
	v_pk_fma_f32 v[148:149], v[20:21], v[166:167], v[148:149] op_sel_hi:[1,0,1]
	v_fma_f32 v167, v166, v36, v164
	v_pk_fma_f32 v[150:151], v[22:23], v[166:167], v[150:151] op_sel_hi:[1,0,1]
	v_fma_f32 v171, v166, v38, v171
	v_cndmask_b32_e64 v162, v162, v168, s[46:47]
	s_lshl_b32 s6, s9, 1
	s_cmp_eq_u32 s6, 0
	s_cbranch_scc1 .Lscan_noy0
	s_add_i32 s6, s6, -1
	s_and_b32 s6, s6, 7
	s_lshl_b32 s6, s6, 10
	v_add_u32_e32 v161, s6, v156
	ds_write_b32 v161, v162
.Lscan_noy0:
	v_pk_fma_f32 v[148:149], v[28:29], v[166:167], v[148:149] op_sel:[0,1,0] op_sel_hi:[1,1,1]
	v_pk_fma_f32 v[150:151], v[30:31], v[166:167], v[150:151] op_sel:[0,1,0] op_sel_hi:[1,1,1]
	v_cndmask_b32_e64 v162, v162, v171, s[38:39]
	v_pk_fma_f32 v[144:145], v[144:145], v[16:17], v[148:149]
	v_pk_fma_f32 v[146:147], v[146:147], v[18:19], v[150:151]
	s_waitcnt lgkmcnt(0)
	v_pk_mul_f32 v[96:97], v[144:145], v[12:13]
	v_pk_mul_f32 v[98:99], v[144:145], v[54:55]
	v_pk_mul_f32 v[100:101], v[144:145], v[58:59]
	v_pk_mul_f32 v[172:173], v[144:145], v[62:63]
	v_pk_fma_f32 v[96:97], v[146:147], v[14:15], v[96:97]
	v_pk_fma_f32 v[98:99], v[146:147], v[56:57], v[98:99]
	v_pk_fma_f32 v[100:101], v[146:147], v[60:61], v[100:101]
	v_pk_fma_f32 v[172:173], v[146:147], v[64:65], v[172:173]
	ds_read_b128 v[0:3], v174 offset:5696
	ds_read_b128 v[4:7], v174 offset:5952
	ds_read_b128 v[8:11], v174 offset:6208
	ds_read_b128 v[12:15], v174 offset:6464
	ds_read_b128 v[16:19], v174 offset:6720
	ds_read_b128 v[20:23], v174 offset:6976
	ds_read_b128 v[24:27], v174 offset:7232
	ds_read_b128 v[28:31], v174 offset:7488
	ds_read_b128 v[32:35], v174 offset:7744
	ds_read_b128 v[36:39], v175 offset:8512
	ds_read_b32 v40, v163 offset:8000
	ds_read_b32 v41, v163 offset:8256
	v_pk_mul_f32 v[148:149], v[78:79], v[94:95] op_sel_hi:[1,0]
	v_pk_mul_f32 v[150:151], v[80:81], v[94:95] op_sel_hi:[1,0]
	v_add_f32_e32 v168, v96, v97
	v_add_f32_e32 v166, v98, v99
	v_add_f32_e32 v169, v100, v101
	v_add_f32_e32 v170, v172, v173
	v_pk_fma_f32 v[148:149], v[86:87], v[94:95], v[148:149] op_sel:[0,1,0] op_sel_hi:[1,1,1]
	v_pk_fma_f32 v[150:151], v[88:89], v[94:95], v[150:151] op_sel:[0,1,0] op_sel_hi:[1,1,1]
	v_add_f32_dpp v168, v168, v168 row_mirror row_mask:0xf bank_mask:0xf bound_ctrl:1
	v_add_f32_dpp v166, v166, v166 row_mirror row_mask:0xf bank_mask:0xf bound_ctrl:1
	v_add_f32_dpp v169, v169, v169 row_mirror row_mask:0xf bank_mask:0xf bound_ctrl:1
	v_add_f32_dpp v170, v170, v170 row_mirror row_mask:0xf bank_mask:0xf bound_ctrl:1
	v_add_f32_dpp v168, v168, v168 row_half_mirror row_mask:0xf bank_mask:0xf bound_ctrl:1
	v_add_f32_dpp v166, v166, v166 row_half_mirror row_mask:0xf bank_mask:0xf bound_ctrl:1
	v_add_f32_dpp v169, v169, v169 row_half_mirror row_mask:0xf bank_mask:0xf bound_ctrl:1
	v_add_f32_dpp v170, v170, v170 row_half_mirror row_mask:0xf bank_mask:0xf bound_ctrl:1
	v_add_f32_dpp v168, v168, v168 quad_perm:[1,0,3,2] row_mask:0xf bank_mask:0xf bound_ctrl:1
	v_add_f32_dpp v166, v166, v166 quad_perm:[1,0,3,2] row_mask:0xf bank_mask:0xf bound_ctrl:1
	v_add_f32_dpp v169, v169, v169 quad_perm:[1,0,3,2] row_mask:0xf bank_mask:0xf bound_ctrl:1
	v_add_f32_dpp v170, v170, v170 quad_perm:[1,0,3,2] row_mask:0xf bank_mask:0xf bound_ctrl:1
	v_add_f32_dpp v168, v168, v168 quad_perm:[2,3,0,1] row_mask:0xf bank_mask:0xf bound_ctrl:1
	v_add_f32_dpp v166, v166, v166 quad_perm:[2,3,0,1] row_mask:0xf bank_mask:0xf bound_ctrl:1
	v_add_f32_dpp v169, v169, v169 quad_perm:[2,3,0,1] row_mask:0xf bank_mask:0xf bound_ctrl:1
	v_add_f32_dpp v170, v170, v170 quad_perm:[2,3,0,1] row_mask:0xf bank_mask:0xf bound_ctrl:1
	v_fma_f32 v164, v94, v91, v169
	v_fma_f32 v171, v94, v93, v170
	v_pk_fma_f32 v[148:149], v[74:75], v[166:167], v[148:149] op_sel_hi:[1,0,1]
	v_fma_f32 v167, v166, v90, v164
	v_pk_fma_f32 v[150:151], v[76:77], v[166:167], v[150:151] op_sel_hi:[1,0,1]
	v_fma_f32 v171, v166, v92, v171
	v_cndmask_b32_e64 v162, v162, v168, s[48:49]
	v_pk_fma_f32 v[148:149], v[82:83], v[166:167], v[148:149] op_sel:[0,1,0] op_sel_hi:[1,1,1]
	v_pk_fma_f32 v[150:151], v[84:85], v[166:167], v[150:151] op_sel:[0,1,0] op_sel_hi:[1,1,1]
	v_cndmask_b32_e64 v162, v162, v171, s[50:51]
	v_pk_fma_f32 v[144:145], v[144:145], v[70:71], v[148:149]
	v_pk_fma_f32 v[146:147], v[146:147], v[72:73], v[150:151]
	s_waitcnt lgkmcnt(0)
	v_pk_mul_f32 v[96:97], v[144:145], v[66:67]
	v_pk_mul_f32 v[98:99], v[144:145], v[0:1]
	v_pk_mul_f32 v[100:101], v[144:145], v[4:5]
	v_pk_mul_f32 v[172:173], v[144:145], v[8:9]
	v_pk_fma_f32 v[96:97], v[146:147], v[68:69], v[96:97]
	v_pk_fma_f32 v[98:99], v[146:147], v[2:3], v[98:99]
	v_pk_fma_f32 v[100:101], v[146:147], v[6:7], v[100:101]
	v_pk_fma_f32 v[172:173], v[146:147], v[10:11], v[172:173]
	ds_read_b128 v[54:57], v174 offset:8544
	ds_read_b128 v[58:61], v174 offset:8800
	ds_read_b128 v[62:65], v174 offset:9056
	ds_read_b128 v[66:69], v174 offset:9312
	ds_read_b128 v[70:73], v174 offset:9568
	ds_read_b128 v[74:77], v174 offset:9824
	ds_read_b128 v[78:81], v174 offset:10080
	ds_read_b128 v[82:85], v174 offset:10336
	ds_read_b128 v[86:89], v174 offset:10592
	ds_read_b128 v[90:93], v175 offset:11360
	ds_read_b32 v94, v163 offset:10848
	ds_read_b32 v95, v163 offset:11104
	v_pk_mul_f32 v[148:149], v[24:25], v[40:41] op_sel_hi:[1,0]
	v_pk_mul_f32 v[150:151], v[26:27], v[40:41] op_sel_hi:[1,0]
	v_add_f32_e32 v168, v96, v97
	v_add_f32_e32 v166, v98, v99
	v_add_f32_e32 v169, v100, v101
	v_add_f32_e32 v170, v172, v173
	v_pk_fma_f32 v[148:149], v[32:33], v[40:41], v[148:149] op_sel:[0,1,0] op_sel_hi:[1,1,1]
	v_pk_fma_f32 v[150:151], v[34:35], v[40:41], v[150:151] op_sel:[0,1,0] op_sel_hi:[1,1,1]
	v_add_f32_dpp v168, v168, v168 row_mirror row_mask:0xf bank_mask:0xf bound_ctrl:1
	v_add_f32_dpp v166, v166, v166 row_mirror row_mask:0xf bank_mask:0xf bound_ctrl:1
	v_add_f32_dpp v169, v169, v169 row_mirror row_mask:0xf bank_mask:0xf bound_ctrl:1
	v_add_f32_dpp v170, v170, v170 row_mirror row_mask:0xf bank_mask:0xf bound_ctrl:1
	v_add_f32_dpp v168, v168, v168 row_half_mirror row_mask:0xf bank_mask:0xf bound_ctrl:1
	v_add_f32_dpp v166, v166, v166 row_half_mirror row_mask:0xf bank_mask:0xf bound_ctrl:1
	v_add_f32_dpp v169, v169, v169 row_half_mirror row_mask:0xf bank_mask:0xf bound_ctrl:1
	v_add_f32_dpp v170, v170, v170 row_half_mirror row_mask:0xf bank_mask:0xf bound_ctrl:1
	v_add_f32_dpp v168, v168, v168 quad_perm:[1,0,3,2] row_mask:0xf bank_mask:0xf bound_ctrl:1
	v_add_f32_dpp v166, v166, v166 quad_perm:[1,0,3,2] row_mask:0xf bank_mask:0xf bound_ctrl:1
	v_add_f32_dpp v169, v169, v169 quad_perm:[1,0,3,2] row_mask:0xf bank_mask:0xf bound_ctrl:1
	v_add_f32_dpp v170, v170, v170 quad_perm:[1,0,3,2] row_mask:0xf bank_mask:0xf bound_ctrl:1
	v_add_f32_dpp v168, v168, v168 quad_perm:[2,3,0,1] row_mask:0xf bank_mask:0xf bound_ctrl:1
	v_add_f32_dpp v166, v166, v166 quad_perm:[2,3,0,1] row_mask:0xf bank_mask:0xf bound_ctrl:1
	v_add_f32_dpp v169, v169, v169 quad_perm:[2,3,0,1] row_mask:0xf bank_mask:0xf bound_ctrl:1
	v_add_f32_dpp v170, v170, v170 quad_perm:[2,3,0,1] row_mask:0xf bank_mask:0xf bound_ctrl:1
	v_fma_f32 v164, v40, v37, v169
	v_fma_f32 v171, v40, v39, v170
	v_pk_fma_f32 v[148:149], v[20:21], v[166:167], v[148:149] op_sel_hi:[1,0,1]
	v_fma_f32 v167, v166, v36, v164
	v_pk_fma_f32 v[150:151], v[22:23], v[166:167], v[150:151] op_sel_hi:[1,0,1]
	v_fma_f32 v171, v166, v38, v171
	v_cndmask_b32_e64 v162, v162, v168, s[52:53]
	v_pk_fma_f32 v[148:149], v[28:29], v[166:167], v[148:149] op_sel:[0,1,0] op_sel_hi:[1,1,1]
	v_pk_fma_f32 v[150:151], v[30:31], v[166:167], v[150:151] op_sel:[0,1,0] op_sel_hi:[1,1,1]
	v_cndmask_b32_e64 v162, v162, v171, s[54:55]
	v_pk_fma_f32 v[144:145], v[144:145], v[16:17], v[148:149]
	v_pk_fma_f32 v[146:147], v[146:147], v[18:19], v[150:151]
	s_waitcnt lgkmcnt(0)
	v_pk_mul_f32 v[96:97], v[144:145], v[12:13]
	v_pk_mul_f32 v[98:99], v[144:145], v[54:55]
	v_pk_mul_f32 v[100:101], v[144:145], v[58:59]
	v_pk_mul_f32 v[172:173], v[144:145], v[62:63]
	v_pk_fma_f32 v[96:97], v[146:147], v[14:15], v[96:97]
	v_pk_fma_f32 v[98:99], v[146:147], v[56:57], v[98:99]
	v_pk_fma_f32 v[100:101], v[146:147], v[60:61], v[100:101]
	v_pk_fma_f32 v[172:173], v[146:147], v[64:65], v[172:173]
	ds_read_b128 v[0:3], v174 offset:11392
	ds_read_b128 v[4:7], v174 offset:11648
	ds_read_b128 v[8:11], v174 offset:11904
	ds_read_b128 v[12:15], v174 offset:12160
	ds_read_b128 v[16:19], v174 offset:12416
	ds_read_b128 v[20:23], v174 offset:12672
	ds_read_b128 v[24:27], v174 offset:12928
	ds_read_b128 v[28:31], v174 offset:13184
	ds_read_b128 v[32:35], v174 offset:13440
	ds_read_b128 v[36:39], v175 offset:14208
	ds_read_b32 v40, v163 offset:13696
	ds_read_b32 v41, v163 offset:13952
	v_pk_mul_f32 v[148:149], v[78:79], v[94:95] op_sel_hi:[1,0]
	v_pk_mul_f32 v[150:151], v[80:81], v[94:95] op_sel_hi:[1,0]
	v_add_f32_e32 v168, v96, v97
	v_add_f32_e32 v166, v98, v99
	v_add_f32_e32 v169, v100, v101
	v_add_f32_e32 v170, v172, v173
	v_pk_fma_f32 v[148:149], v[86:87], v[94:95], v[148:149] op_sel:[0,1,0] op_sel_hi:[1,1,1]
	v_pk_fma_f32 v[150:151], v[88:89], v[94:95], v[150:151] op_sel:[0,1,0] op_sel_hi:[1,1,1]
	v_add_f32_dpp v168, v168, v168 row_mirror row_mask:0xf bank_mask:0xf bound_ctrl:1
	v_add_f32_dpp v166, v166, v166 row_mirror row_mask:0xf bank_mask:0xf bound_ctrl:1
	v_add_f32_dpp v169, v169, v169 row_mirror row_mask:0xf bank_mask:0xf bound_ctrl:1
	v_add_f32_dpp v170, v170, v170 row_mirror row_mask:0xf bank_mask:0xf bound_ctrl:1
	v_add_f32_dpp v168, v168, v168 row_half_mirror row_mask:0xf bank_mask:0xf bound_ctrl:1
	v_add_f32_dpp v166, v166, v166 row_half_mirror row_mask:0xf bank_mask:0xf bound_ctrl:1
	v_add_f32_dpp v169, v169, v169 row_half_mirror row_mask:0xf bank_mask:0xf bound_ctrl:1
	v_add_f32_dpp v170, v170, v170 row_half_mirror row_mask:0xf bank_mask:0xf bound_ctrl:1
	v_add_f32_dpp v168, v168, v168 quad_perm:[1,0,3,2] row_mask:0xf bank_mask:0xf bound_ctrl:1
	v_add_f32_dpp v166, v166, v166 quad_perm:[1,0,3,2] row_mask:0xf bank_mask:0xf bound_ctrl:1
	v_add_f32_dpp v169, v169, v169 quad_perm:[1,0,3,2] row_mask:0xf bank_mask:0xf bound_ctrl:1
	v_add_f32_dpp v170, v170, v170 quad_perm:[1,0,3,2] row_mask:0xf bank_mask:0xf bound_ctrl:1
	v_add_f32_dpp v168, v168, v168 quad_perm:[2,3,0,1] row_mask:0xf bank_mask:0xf bound_ctrl:1
	v_add_f32_dpp v166, v166, v166 quad_perm:[2,3,0,1] row_mask:0xf bank_mask:0xf bound_ctrl:1
	v_add_f32_dpp v169, v169, v169 quad_perm:[2,3,0,1] row_mask:0xf bank_mask:0xf bound_ctrl:1
	v_add_f32_dpp v170, v170, v170 quad_perm:[2,3,0,1] row_mask:0xf bank_mask:0xf bound_ctrl:1
	v_fma_f32 v164, v94, v91, v169
	v_fma_f32 v171, v94, v93, v170
	v_pk_fma_f32 v[148:149], v[74:75], v[166:167], v[148:149] op_sel_hi:[1,0,1]
	v_fma_f32 v167, v166, v90, v164
	v_pk_fma_f32 v[150:151], v[76:77], v[166:167], v[150:151] op_sel_hi:[1,0,1]
	v_fma_f32 v171, v166, v92, v171
	v_cndmask_b32_e64 v162, v162, v168, s[56:57]
	v_pk_fma_f32 v[148:149], v[82:83], v[166:167], v[148:149] op_sel:[0,1,0] op_sel_hi:[1,1,1]
	v_pk_fma_f32 v[150:151], v[84:85], v[166:167], v[150:151] op_sel:[0,1,0] op_sel_hi:[1,1,1]
	v_cndmask_b32_e64 v162, v162, v171, s[58:59]
	v_pk_fma_f32 v[144:145], v[144:145], v[70:71], v[148:149]
	v_pk_fma_f32 v[146:147], v[146:147], v[72:73], v[150:151]
	s_waitcnt lgkmcnt(0)
	v_pk_mul_f32 v[96:97], v[144:145], v[66:67]
	v_pk_mul_f32 v[98:99], v[144:145], v[0:1]
	v_pk_mul_f32 v[100:101], v[144:145], v[4:5]
	v_pk_mul_f32 v[172:173], v[144:145], v[8:9]
	v_pk_fma_f32 v[96:97], v[146:147], v[68:69], v[96:97]
	v_pk_fma_f32 v[98:99], v[146:147], v[2:3], v[98:99]
	v_pk_fma_f32 v[100:101], v[146:147], v[6:7], v[100:101]
	v_pk_fma_f32 v[172:173], v[146:147], v[10:11], v[172:173]
	ds_read_b128 v[54:57], v174 offset:14240
	ds_read_b128 v[58:61], v174 offset:14496
	ds_read_b128 v[62:65], v174 offset:14752
	ds_read_b128 v[66:69], v174 offset:15008
	ds_read_b128 v[70:73], v174 offset:15264
	ds_read_b128 v[74:77], v174 offset:15520
	ds_read_b128 v[78:81], v174 offset:15776
	ds_read_b128 v[82:85], v174 offset:16032
	ds_read_b128 v[86:89], v174 offset:16288
	ds_read_b128 v[90:93], v175 offset:17056
	ds_read_b32 v94, v163 offset:16544
	ds_read_b32 v95, v163 offset:16800
	v_pk_mul_f32 v[148:149], v[24:25], v[40:41] op_sel_hi:[1,0]
	v_pk_mul_f32 v[150:151], v[26:27], v[40:41] op_sel_hi:[1,0]
	v_add_f32_e32 v168, v96, v97
	v_add_f32_e32 v166, v98, v99
	v_add_f32_e32 v169, v100, v101
	v_add_f32_e32 v170, v172, v173
	v_pk_fma_f32 v[148:149], v[32:33], v[40:41], v[148:149] op_sel:[0,1,0] op_sel_hi:[1,1,1]
	v_pk_fma_f32 v[150:151], v[34:35], v[40:41], v[150:151] op_sel:[0,1,0] op_sel_hi:[1,1,1]
	v_add_f32_dpp v168, v168, v168 row_mirror row_mask:0xf bank_mask:0xf bound_ctrl:1
	v_add_f32_dpp v166, v166, v166 row_mirror row_mask:0xf bank_mask:0xf bound_ctrl:1
	v_add_f32_dpp v169, v169, v169 row_mirror row_mask:0xf bank_mask:0xf bound_ctrl:1
	v_add_f32_dpp v170, v170, v170 row_mirror row_mask:0xf bank_mask:0xf bound_ctrl:1
	v_add_f32_dpp v168, v168, v168 row_half_mirror row_mask:0xf bank_mask:0xf bound_ctrl:1
	v_add_f32_dpp v166, v166, v166 row_half_mirror row_mask:0xf bank_mask:0xf bound_ctrl:1
	v_add_f32_dpp v169, v169, v169 row_half_mirror row_mask:0xf bank_mask:0xf bound_ctrl:1
	v_add_f32_dpp v170, v170, v170 row_half_mirror row_mask:0xf bank_mask:0xf bound_ctrl:1
	v_add_f32_dpp v168, v168, v168 quad_perm:[1,0,3,2] row_mask:0xf bank_mask:0xf bound_ctrl:1
	v_add_f32_dpp v166, v166, v166 quad_perm:[1,0,3,2] row_mask:0xf bank_mask:0xf bound_ctrl:1
	v_add_f32_dpp v169, v169, v169 quad_perm:[1,0,3,2] row_mask:0xf bank_mask:0xf bound_ctrl:1
	v_add_f32_dpp v170, v170, v170 quad_perm:[1,0,3,2] row_mask:0xf bank_mask:0xf bound_ctrl:1
	v_add_f32_dpp v168, v168, v168 quad_perm:[2,3,0,1] row_mask:0xf bank_mask:0xf bound_ctrl:1
	v_add_f32_dpp v166, v166, v166 quad_perm:[2,3,0,1] row_mask:0xf bank_mask:0xf bound_ctrl:1
	v_add_f32_dpp v169, v169, v169 quad_perm:[2,3,0,1] row_mask:0xf bank_mask:0xf bound_ctrl:1
	v_add_f32_dpp v170, v170, v170 quad_perm:[2,3,0,1] row_mask:0xf bank_mask:0xf bound_ctrl:1
	v_fma_f32 v164, v40, v37, v169
	v_fma_f32 v171, v40, v39, v170
	v_pk_fma_f32 v[148:149], v[20:21], v[166:167], v[148:149] op_sel_hi:[1,0,1]
	v_fma_f32 v167, v166, v36, v164
	v_pk_fma_f32 v[150:151], v[22:23], v[166:167], v[150:151] op_sel_hi:[1,0,1]
	v_fma_f32 v171, v166, v38, v171
	v_cndmask_b32_e64 v162, v162, v168, s[60:61]
	v_pk_fma_f32 v[148:149], v[28:29], v[166:167], v[148:149] op_sel:[0,1,0] op_sel_hi:[1,1,1]
	v_pk_fma_f32 v[150:151], v[30:31], v[166:167], v[150:151] op_sel:[0,1,0] op_sel_hi:[1,1,1]
	v_cndmask_b32_e64 v162, v162, v171, s[62:63]
	v_pk_fma_f32 v[144:145], v[144:145], v[16:17], v[148:149]
	v_pk_fma_f32 v[146:147], v[146:147], v[18:19], v[150:151]
	s_waitcnt lgkmcnt(0)
	v_pk_mul_f32 v[96:97], v[144:145], v[12:13]
	v_pk_mul_f32 v[98:99], v[144:145], v[54:55]
	v_pk_mul_f32 v[100:101], v[144:145], v[58:59]
	v_pk_mul_f32 v[172:173], v[144:145], v[62:63]
	v_pk_fma_f32 v[96:97], v[146:147], v[14:15], v[96:97]
	v_pk_fma_f32 v[98:99], v[146:147], v[56:57], v[98:99]
	v_pk_fma_f32 v[100:101], v[146:147], v[60:61], v[100:101]
	v_pk_fma_f32 v[172:173], v[146:147], v[64:65], v[172:173]
	ds_read_b128 v[0:3], v174 offset:17088
	ds_read_b128 v[4:7], v174 offset:17344
	ds_read_b128 v[8:11], v174 offset:17600
	ds_read_b128 v[12:15], v174 offset:17856
	ds_read_b128 v[16:19], v174 offset:18112
	ds_read_b128 v[20:23], v174 offset:18368
	ds_read_b128 v[24:27], v174 offset:18624
	ds_read_b128 v[28:31], v174 offset:18880
	ds_read_b128 v[32:35], v174 offset:19136
	ds_read_b128 v[36:39], v175 offset:19904
	ds_read_b32 v40, v163 offset:19392
	ds_read_b32 v41, v163 offset:19648
	v_pk_mul_f32 v[148:149], v[78:79], v[94:95] op_sel_hi:[1,0]
	v_pk_mul_f32 v[150:151], v[80:81], v[94:95] op_sel_hi:[1,0]
	v_add_f32_e32 v168, v96, v97
	v_add_f32_e32 v166, v98, v99
	v_add_f32_e32 v169, v100, v101
	v_add_f32_e32 v170, v172, v173
	v_pk_fma_f32 v[148:149], v[86:87], v[94:95], v[148:149] op_sel:[0,1,0] op_sel_hi:[1,1,1]
	v_pk_fma_f32 v[150:151], v[88:89], v[94:95], v[150:151] op_sel:[0,1,0] op_sel_hi:[1,1,1]
	v_add_f32_dpp v168, v168, v168 row_mirror row_mask:0xf bank_mask:0xf bound_ctrl:1
	v_add_f32_dpp v166, v166, v166 row_mirror row_mask:0xf bank_mask:0xf bound_ctrl:1
	v_add_f32_dpp v169, v169, v169 row_mirror row_mask:0xf bank_mask:0xf bound_ctrl:1
	v_add_f32_dpp v170, v170, v170 row_mirror row_mask:0xf bank_mask:0xf bound_ctrl:1
	v_add_f32_dpp v168, v168, v168 row_half_mirror row_mask:0xf bank_mask:0xf bound_ctrl:1
	v_add_f32_dpp v166, v166, v166 row_half_mirror row_mask:0xf bank_mask:0xf bound_ctrl:1
	v_add_f32_dpp v169, v169, v169 row_half_mirror row_mask:0xf bank_mask:0xf bound_ctrl:1
	v_add_f32_dpp v170, v170, v170 row_half_mirror row_mask:0xf bank_mask:0xf bound_ctrl:1
	v_add_f32_dpp v168, v168, v168 quad_perm:[1,0,3,2] row_mask:0xf bank_mask:0xf bound_ctrl:1
	v_add_f32_dpp v166, v166, v166 quad_perm:[1,0,3,2] row_mask:0xf bank_mask:0xf bound_ctrl:1
	v_add_f32_dpp v169, v169, v169 quad_perm:[1,0,3,2] row_mask:0xf bank_mask:0xf bound_ctrl:1
	v_add_f32_dpp v170, v170, v170 quad_perm:[1,0,3,2] row_mask:0xf bank_mask:0xf bound_ctrl:1
	v_add_f32_dpp v168, v168, v168 quad_perm:[2,3,0,1] row_mask:0xf bank_mask:0xf bound_ctrl:1
	v_add_f32_dpp v166, v166, v166 quad_perm:[2,3,0,1] row_mask:0xf bank_mask:0xf bound_ctrl:1
	v_add_f32_dpp v169, v169, v169 quad_perm:[2,3,0,1] row_mask:0xf bank_mask:0xf bound_ctrl:1
	v_add_f32_dpp v170, v170, v170 quad_perm:[2,3,0,1] row_mask:0xf bank_mask:0xf bound_ctrl:1
	v_fma_f32 v164, v94, v91, v169
	v_fma_f32 v171, v94, v93, v170
	v_pk_fma_f32 v[148:149], v[74:75], v[166:167], v[148:149] op_sel_hi:[1,0,1]
	v_fma_f32 v167, v166, v90, v164
	v_pk_fma_f32 v[150:151], v[76:77], v[166:167], v[150:151] op_sel_hi:[1,0,1]
	v_fma_f32 v171, v166, v92, v171
	v_cndmask_b32_e64 v162, v162, v168, s[64:65]
	v_pk_fma_f32 v[148:149], v[82:83], v[166:167], v[148:149] op_sel:[0,1,0] op_sel_hi:[1,1,1]
	v_pk_fma_f32 v[150:151], v[84:85], v[166:167], v[150:151] op_sel:[0,1,0] op_sel_hi:[1,1,1]
	v_cndmask_b32_e64 v162, v162, v171, s[66:67]
	v_pk_fma_f32 v[144:145], v[144:145], v[70:71], v[148:149]
	v_pk_fma_f32 v[146:147], v[146:147], v[72:73], v[150:151]
	s_waitcnt lgkmcnt(0)
	v_pk_mul_f32 v[96:97], v[144:145], v[66:67]
	v_pk_mul_f32 v[98:99], v[144:145], v[0:1]
	v_pk_mul_f32 v[100:101], v[144:145], v[4:5]
	v_pk_mul_f32 v[172:173], v[144:145], v[8:9]
	v_pk_fma_f32 v[96:97], v[146:147], v[68:69], v[96:97]
	v_pk_fma_f32 v[98:99], v[146:147], v[2:3], v[98:99]
	v_pk_fma_f32 v[100:101], v[146:147], v[6:7], v[100:101]
	v_pk_fma_f32 v[172:173], v[146:147], v[10:11], v[172:173]
	ds_read_b128 v[54:57], v174 offset:19936
	ds_read_b128 v[58:61], v174 offset:20192
	ds_read_b128 v[62:65], v174 offset:20448
	ds_read_b128 v[66:69], v174 offset:20704
	ds_read_b128 v[70:73], v174 offset:20960
	ds_read_b128 v[74:77], v174 offset:21216
	ds_read_b128 v[78:81], v174 offset:21472
	ds_read_b128 v[82:85], v174 offset:21728
	ds_read_b128 v[86:89], v174 offset:21984
	ds_read_b128 v[90:93], v175 offset:22752
	ds_read_b32 v94, v163 offset:22240
	ds_read_b32 v95, v163 offset:22496
	v_pk_mul_f32 v[148:149], v[24:25], v[40:41] op_sel_hi:[1,0]
	v_pk_mul_f32 v[150:151], v[26:27], v[40:41] op_sel_hi:[1,0]
	v_add_f32_e32 v168, v96, v97
	v_add_f32_e32 v166, v98, v99
	v_add_f32_e32 v169, v100, v101
	v_add_f32_e32 v170, v172, v173
	v_pk_fma_f32 v[148:149], v[32:33], v[40:41], v[148:149] op_sel:[0,1,0] op_sel_hi:[1,1,1]
	v_pk_fma_f32 v[150:151], v[34:35], v[40:41], v[150:151] op_sel:[0,1,0] op_sel_hi:[1,1,1]
	v_add_f32_dpp v168, v168, v168 row_mirror row_mask:0xf bank_mask:0xf bound_ctrl:1
	v_add_f32_dpp v166, v166, v166 row_mirror row_mask:0xf bank_mask:0xf bound_ctrl:1
	v_add_f32_dpp v169, v169, v169 row_mirror row_mask:0xf bank_mask:0xf bound_ctrl:1
	v_add_f32_dpp v170, v170, v170 row_mirror row_mask:0xf bank_mask:0xf bound_ctrl:1
	v_add_f32_dpp v168, v168, v168 row_half_mirror row_mask:0xf bank_mask:0xf bound_ctrl:1
	v_add_f32_dpp v166, v166, v166 row_half_mirror row_mask:0xf bank_mask:0xf bound_ctrl:1
	v_add_f32_dpp v169, v169, v169 row_half_mirror row_mask:0xf bank_mask:0xf bound_ctrl:1
	v_add_f32_dpp v170, v170, v170 row_half_mirror row_mask:0xf bank_mask:0xf bound_ctrl:1
	v_add_f32_dpp v168, v168, v168 quad_perm:[1,0,3,2] row_mask:0xf bank_mask:0xf bound_ctrl:1
	v_add_f32_dpp v166, v166, v166 quad_perm:[1,0,3,2] row_mask:0xf bank_mask:0xf bound_ctrl:1
	v_add_f32_dpp v169, v169, v169 quad_perm:[1,0,3,2] row_mask:0xf bank_mask:0xf bound_ctrl:1
	v_add_f32_dpp v170, v170, v170 quad_perm:[1,0,3,2] row_mask:0xf bank_mask:0xf bound_ctrl:1
	v_add_f32_dpp v168, v168, v168 quad_perm:[2,3,0,1] row_mask:0xf bank_mask:0xf bound_ctrl:1
	v_add_f32_dpp v166, v166, v166 quad_perm:[2,3,0,1] row_mask:0xf bank_mask:0xf bound_ctrl:1
	v_add_f32_dpp v169, v169, v169 quad_perm:[2,3,0,1] row_mask:0xf bank_mask:0xf bound_ctrl:1
	v_add_f32_dpp v170, v170, v170 quad_perm:[2,3,0,1] row_mask:0xf bank_mask:0xf bound_ctrl:1
	v_fma_f32 v164, v40, v37, v169
	v_fma_f32 v171, v40, v39, v170
	v_pk_fma_f32 v[148:149], v[20:21], v[166:167], v[148:149] op_sel_hi:[1,0,1]
	v_fma_f32 v167, v166, v36, v164
	v_pk_fma_f32 v[150:151], v[22:23], v[166:167], v[150:151] op_sel_hi:[1,0,1]
	v_fma_f32 v171, v166, v38, v171
	v_cndmask_b32_e64 v162, v162, v168, s[68:69]
	v_pk_fma_f32 v[148:149], v[28:29], v[166:167], v[148:149] op_sel:[0,1,0] op_sel_hi:[1,1,1]
	v_pk_fma_f32 v[150:151], v[30:31], v[166:167], v[150:151] op_sel:[0,1,0] op_sel_hi:[1,1,1]
	v_cndmask_b32_e64 v162, v162, v171, s[70:71]
	v_pk_fma_f32 v[144:145], v[144:145], v[16:17], v[148:149]
	v_pk_fma_f32 v[146:147], v[146:147], v[18:19], v[150:151]
	s_waitcnt lgkmcnt(0)
	v_pk_mul_f32 v[96:97], v[144:145], v[12:13]
	v_pk_mul_f32 v[98:99], v[144:145], v[54:55]
	v_pk_mul_f32 v[100:101], v[144:145], v[58:59]
	v_pk_mul_f32 v[172:173], v[144:145], v[62:63]
	v_pk_fma_f32 v[96:97], v[146:147], v[14:15], v[96:97]
	v_pk_fma_f32 v[98:99], v[146:147], v[56:57], v[98:99]
	v_pk_fma_f32 v[100:101], v[146:147], v[60:61], v[100:101]
	v_pk_fma_f32 v[172:173], v[146:147], v[64:65], v[172:173]
	ds_read_b128 v[0:3], v174 offset:22784
	ds_read_b128 v[4:7], v174 offset:23040
	ds_read_b128 v[8:11], v174 offset:23296
	ds_read_b128 v[12:15], v174 offset:23552
	ds_read_b128 v[16:19], v174 offset:23808
	ds_read_b128 v[20:23], v174 offset:24064
	ds_read_b128 v[24:27], v174 offset:24320
	ds_read_b128 v[28:31], v174 offset:24576
	ds_read_b128 v[32:35], v174 offset:24832
	ds_read_b128 v[36:39], v175 offset:25600
	ds_read_b32 v40, v163 offset:25088
	ds_read_b32 v41, v163 offset:25344
	v_pk_mul_f32 v[148:149], v[78:79], v[94:95] op_sel_hi:[1,0]
	v_pk_mul_f32 v[150:151], v[80:81], v[94:95] op_sel_hi:[1,0]
	v_add_f32_e32 v168, v96, v97
	v_add_f32_e32 v166, v98, v99
	v_add_f32_e32 v169, v100, v101
	v_add_f32_e32 v170, v172, v173
	v_pk_fma_f32 v[148:149], v[86:87], v[94:95], v[148:149] op_sel:[0,1,0] op_sel_hi:[1,1,1]
	v_pk_fma_f32 v[150:151], v[88:89], v[94:95], v[150:151] op_sel:[0,1,0] op_sel_hi:[1,1,1]
	v_add_f32_dpp v168, v168, v168 row_mirror row_mask:0xf bank_mask:0xf bound_ctrl:1
	v_add_f32_dpp v166, v166, v166 row_mirror row_mask:0xf bank_mask:0xf bound_ctrl:1
	v_add_f32_dpp v169, v169, v169 row_mirror row_mask:0xf bank_mask:0xf bound_ctrl:1
	v_add_f32_dpp v170, v170, v170 row_mirror row_mask:0xf bank_mask:0xf bound_ctrl:1
	v_add_f32_dpp v168, v168, v168 row_half_mirror row_mask:0xf bank_mask:0xf bound_ctrl:1
	v_add_f32_dpp v166, v166, v166 row_half_mirror row_mask:0xf bank_mask:0xf bound_ctrl:1
	v_add_f32_dpp v169, v169, v169 row_half_mirror row_mask:0xf bank_mask:0xf bound_ctrl:1
	v_add_f32_dpp v170, v170, v170 row_half_mirror row_mask:0xf bank_mask:0xf bound_ctrl:1
	v_add_f32_dpp v168, v168, v168 quad_perm:[1,0,3,2] row_mask:0xf bank_mask:0xf bound_ctrl:1
	v_add_f32_dpp v166, v166, v166 quad_perm:[1,0,3,2] row_mask:0xf bank_mask:0xf bound_ctrl:1
	v_add_f32_dpp v169, v169, v169 quad_perm:[1,0,3,2] row_mask:0xf bank_mask:0xf bound_ctrl:1
	v_add_f32_dpp v170, v170, v170 quad_perm:[1,0,3,2] row_mask:0xf bank_mask:0xf bound_ctrl:1
	v_add_f32_dpp v168, v168, v168 quad_perm:[2,3,0,1] row_mask:0xf bank_mask:0xf bound_ctrl:1
	v_add_f32_dpp v166, v166, v166 quad_perm:[2,3,0,1] row_mask:0xf bank_mask:0xf bound_ctrl:1
	v_add_f32_dpp v169, v169, v169 quad_perm:[2,3,0,1] row_mask:0xf bank_mask:0xf bound_ctrl:1
	v_add_f32_dpp v170, v170, v170 quad_perm:[2,3,0,1] row_mask:0xf bank_mask:0xf bound_ctrl:1
	v_fma_f32 v164, v94, v91, v169
	v_fma_f32 v171, v94, v93, v170
	v_pk_fma_f32 v[148:149], v[74:75], v[166:167], v[148:149] op_sel_hi:[1,0,1]
	v_fma_f32 v167, v166, v90, v164
	v_pk_fma_f32 v[150:151], v[76:77], v[166:167], v[150:151] op_sel_hi:[1,0,1]
	v_fma_f32 v171, v166, v92, v171
	v_cndmask_b32_e64 v162, v162, v168, s[44:45]
	v_pk_fma_f32 v[148:149], v[82:83], v[166:167], v[148:149] op_sel:[0,1,0] op_sel_hi:[1,1,1]
	v_pk_fma_f32 v[150:151], v[84:85], v[166:167], v[150:151] op_sel:[0,1,0] op_sel_hi:[1,1,1]
	v_cndmask_b32_e64 v162, v162, v171, s[42:43]
	v_pk_fma_f32 v[144:145], v[144:145], v[70:71], v[148:149]
	v_pk_fma_f32 v[146:147], v[146:147], v[72:73], v[150:151]
	s_waitcnt lgkmcnt(0)
	v_pk_mul_f32 v[96:97], v[144:145], v[66:67]
	v_pk_mul_f32 v[98:99], v[144:145], v[0:1]
	v_pk_mul_f32 v[100:101], v[144:145], v[4:5]
	v_pk_mul_f32 v[172:173], v[144:145], v[8:9]
	v_pk_fma_f32 v[96:97], v[146:147], v[68:69], v[96:97]
	v_pk_fma_f32 v[98:99], v[146:147], v[2:3], v[98:99]
	v_pk_fma_f32 v[100:101], v[146:147], v[6:7], v[100:101]
	v_pk_fma_f32 v[172:173], v[146:147], v[10:11], v[172:173]
	ds_read_b128 v[54:57], v174 offset:25632
	ds_read_b128 v[58:61], v174 offset:25888
	ds_read_b128 v[62:65], v174 offset:26144
	ds_read_b128 v[66:69], v174 offset:26400
	ds_read_b128 v[70:73], v174 offset:26656
	ds_read_b128 v[74:77], v174 offset:26912
	ds_read_b128 v[78:81], v174 offset:27168
	ds_read_b128 v[82:85], v174 offset:27424
	ds_read_b128 v[86:89], v174 offset:27680
	ds_read_b128 v[90:93], v175 offset:28448
	ds_read_b32 v94, v163 offset:27936
	ds_read_b32 v95, v163 offset:28192
	v_pk_mul_f32 v[148:149], v[24:25], v[40:41] op_sel_hi:[1,0]
	v_pk_mul_f32 v[150:151], v[26:27], v[40:41] op_sel_hi:[1,0]
	v_add_f32_e32 v168, v96, v97
	v_add_f32_e32 v166, v98, v99
	v_add_f32_e32 v169, v100, v101
	v_add_f32_e32 v170, v172, v173
	v_pk_fma_f32 v[148:149], v[32:33], v[40:41], v[148:149] op_sel:[0,1,0] op_sel_hi:[1,1,1]
	v_pk_fma_f32 v[150:151], v[34:35], v[40:41], v[150:151] op_sel:[0,1,0] op_sel_hi:[1,1,1]
	v_add_f32_dpp v168, v168, v168 row_mirror row_mask:0xf bank_mask:0xf bound_ctrl:1
	v_add_f32_dpp v166, v166, v166 row_mirror row_mask:0xf bank_mask:0xf bound_ctrl:1
	v_add_f32_dpp v169, v169, v169 row_mirror row_mask:0xf bank_mask:0xf bound_ctrl:1
	v_add_f32_dpp v170, v170, v170 row_mirror row_mask:0xf bank_mask:0xf bound_ctrl:1
	v_add_f32_dpp v168, v168, v168 row_half_mirror row_mask:0xf bank_mask:0xf bound_ctrl:1
	v_add_f32_dpp v166, v166, v166 row_half_mirror row_mask:0xf bank_mask:0xf bound_ctrl:1
	v_add_f32_dpp v169, v169, v169 row_half_mirror row_mask:0xf bank_mask:0xf bound_ctrl:1
	v_add_f32_dpp v170, v170, v170 row_half_mirror row_mask:0xf bank_mask:0xf bound_ctrl:1
	v_add_f32_dpp v168, v168, v168 quad_perm:[1,0,3,2] row_mask:0xf bank_mask:0xf bound_ctrl:1
	v_add_f32_dpp v166, v166, v166 quad_perm:[1,0,3,2] row_mask:0xf bank_mask:0xf bound_ctrl:1
	v_add_f32_dpp v169, v169, v169 quad_perm:[1,0,3,2] row_mask:0xf bank_mask:0xf bound_ctrl:1
	v_add_f32_dpp v170, v170, v170 quad_perm:[1,0,3,2] row_mask:0xf bank_mask:0xf bound_ctrl:1
	v_add_f32_dpp v168, v168, v168 quad_perm:[2,3,0,1] row_mask:0xf bank_mask:0xf bound_ctrl:1
	v_add_f32_dpp v166, v166, v166 quad_perm:[2,3,0,1] row_mask:0xf bank_mask:0xf bound_ctrl:1
	v_add_f32_dpp v169, v169, v169 quad_perm:[2,3,0,1] row_mask:0xf bank_mask:0xf bound_ctrl:1
	v_add_f32_dpp v170, v170, v170 quad_perm:[2,3,0,1] row_mask:0xf bank_mask:0xf bound_ctrl:1
	v_fma_f32 v164, v40, v37, v169
	v_fma_f32 v171, v40, v39, v170
	v_pk_fma_f32 v[148:149], v[20:21], v[166:167], v[148:149] op_sel_hi:[1,0,1]
	v_fma_f32 v167, v166, v36, v164
	v_pk_fma_f32 v[150:151], v[22:23], v[166:167], v[150:151] op_sel_hi:[1,0,1]
	v_fma_f32 v171, v166, v38, v171
	v_cndmask_b32_e64 v162, v162, v168, s[46:47]
	s_lshl_b32 s6, s9, 1
	s_add_i32 s6, s6, 1
	s_add_i32 s6, s6, -1
	s_and_b32 s6, s6, 7
	s_lshl_b32 s6, s6, 10
	v_add_u32_e32 v161, s6, v156
	ds_write_b32 v161, v162
	v_pk_fma_f32 v[148:149], v[28:29], v[166:167], v[148:149] op_sel:[0,1,0] op_sel_hi:[1,1,1]
	v_pk_fma_f32 v[150:151], v[30:31], v[166:167], v[150:151] op_sel:[0,1,0] op_sel_hi:[1,1,1]
	v_cndmask_b32_e64 v162, v162, v171, s[38:39]
	v_pk_fma_f32 v[144:145], v[144:145], v[16:17], v[148:149]
	v_pk_fma_f32 v[146:147], v[146:147], v[18:19], v[150:151]
	s_waitcnt lgkmcnt(0)
	v_pk_mul_f32 v[96:97], v[144:145], v[12:13]
	v_pk_mul_f32 v[98:99], v[144:145], v[54:55]
	v_pk_mul_f32 v[100:101], v[144:145], v[58:59]
	v_pk_mul_f32 v[172:173], v[144:145], v[62:63]
	v_pk_fma_f32 v[96:97], v[146:147], v[14:15], v[96:97]
	v_pk_fma_f32 v[98:99], v[146:147], v[56:57], v[98:99]
	v_pk_fma_f32 v[100:101], v[146:147], v[60:61], v[100:101]
	v_pk_fma_f32 v[172:173], v[146:147], v[64:65], v[172:173]
	ds_read_b128 v[0:3], v174 offset:28480
	ds_read_b128 v[4:7], v174 offset:28736
	ds_read_b128 v[8:11], v174 offset:28992
	ds_read_b128 v[12:15], v174 offset:29248
	ds_read_b128 v[16:19], v174 offset:29504
	ds_read_b128 v[20:23], v174 offset:29760
	ds_read_b128 v[24:27], v174 offset:30016
	ds_read_b128 v[28:31], v174 offset:30272
	ds_read_b128 v[32:35], v174 offset:30528
	ds_read_b128 v[36:39], v175 offset:31296
	ds_read_b32 v40, v163 offset:30784
	ds_read_b32 v41, v163 offset:31040
	v_pk_mul_f32 v[148:149], v[78:79], v[94:95] op_sel_hi:[1,0]
	v_pk_mul_f32 v[150:151], v[80:81], v[94:95] op_sel_hi:[1,0]
	v_add_f32_e32 v168, v96, v97
	v_add_f32_e32 v166, v98, v99
	v_add_f32_e32 v169, v100, v101
	v_add_f32_e32 v170, v172, v173
	v_pk_fma_f32 v[148:149], v[86:87], v[94:95], v[148:149] op_sel:[0,1,0] op_sel_hi:[1,1,1]
	v_pk_fma_f32 v[150:151], v[88:89], v[94:95], v[150:151] op_sel:[0,1,0] op_sel_hi:[1,1,1]
	v_add_f32_dpp v168, v168, v168 row_mirror row_mask:0xf bank_mask:0xf bound_ctrl:1
	v_add_f32_dpp v166, v166, v166 row_mirror row_mask:0xf bank_mask:0xf bound_ctrl:1
	v_add_f32_dpp v169, v169, v169 row_mirror row_mask:0xf bank_mask:0xf bound_ctrl:1
	v_add_f32_dpp v170, v170, v170 row_mirror row_mask:0xf bank_mask:0xf bound_ctrl:1
	v_add_f32_dpp v168, v168, v168 row_half_mirror row_mask:0xf bank_mask:0xf bound_ctrl:1
	v_add_f32_dpp v166, v166, v166 row_half_mirror row_mask:0xf bank_mask:0xf bound_ctrl:1
	v_add_f32_dpp v169, v169, v169 row_half_mirror row_mask:0xf bank_mask:0xf bound_ctrl:1
	v_add_f32_dpp v170, v170, v170 row_half_mirror row_mask:0xf bank_mask:0xf bound_ctrl:1
	v_add_f32_dpp v168, v168, v168 quad_perm:[1,0,3,2] row_mask:0xf bank_mask:0xf bound_ctrl:1
	v_add_f32_dpp v166, v166, v166 quad_perm:[1,0,3,2] row_mask:0xf bank_mask:0xf bound_ctrl:1
	v_add_f32_dpp v169, v169, v169 quad_perm:[1,0,3,2] row_mask:0xf bank_mask:0xf bound_ctrl:1
	v_add_f32_dpp v170, v170, v170 quad_perm:[1,0,3,2] row_mask:0xf bank_mask:0xf bound_ctrl:1
	v_add_f32_dpp v168, v168, v168 quad_perm:[2,3,0,1] row_mask:0xf bank_mask:0xf bound_ctrl:1
	v_add_f32_dpp v166, v166, v166 quad_perm:[2,3,0,1] row_mask:0xf bank_mask:0xf bound_ctrl:1
	v_add_f32_dpp v169, v169, v169 quad_perm:[2,3,0,1] row_mask:0xf bank_mask:0xf bound_ctrl:1
	v_add_f32_dpp v170, v170, v170 quad_perm:[2,3,0,1] row_mask:0xf bank_mask:0xf bound_ctrl:1
	v_fma_f32 v164, v94, v91, v169
	v_fma_f32 v171, v94, v93, v170
	v_pk_fma_f32 v[148:149], v[74:75], v[166:167], v[148:149] op_sel_hi:[1,0,1]
	v_fma_f32 v167, v166, v90, v164
	v_pk_fma_f32 v[150:151], v[76:77], v[166:167], v[150:151] op_sel_hi:[1,0,1]
	v_fma_f32 v171, v166, v92, v171
	v_cndmask_b32_e64 v162, v162, v168, s[48:49]
	v_pk_fma_f32 v[148:149], v[82:83], v[166:167], v[148:149] op_sel:[0,1,0] op_sel_hi:[1,1,1]
	v_pk_fma_f32 v[150:151], v[84:85], v[166:167], v[150:151] op_sel:[0,1,0] op_sel_hi:[1,1,1]
	v_cndmask_b32_e64 v162, v162, v171, s[50:51]
	v_pk_fma_f32 v[144:145], v[144:145], v[70:71], v[148:149]
	v_pk_fma_f32 v[146:147], v[146:147], v[72:73], v[150:151]
	s_waitcnt lgkmcnt(0)
	v_pk_mul_f32 v[96:97], v[144:145], v[66:67]
	v_pk_mul_f32 v[98:99], v[144:145], v[0:1]
	v_pk_mul_f32 v[100:101], v[144:145], v[4:5]
	v_pk_mul_f32 v[172:173], v[144:145], v[8:9]
	v_pk_fma_f32 v[96:97], v[146:147], v[68:69], v[96:97]
	v_pk_fma_f32 v[98:99], v[146:147], v[2:3], v[98:99]
	v_pk_fma_f32 v[100:101], v[146:147], v[6:7], v[100:101]
	v_pk_fma_f32 v[172:173], v[146:147], v[10:11], v[172:173]
	ds_read_b128 v[54:57], v174 offset:31328
	ds_read_b128 v[58:61], v174 offset:31584
	ds_read_b128 v[62:65], v174 offset:31840
	ds_read_b128 v[66:69], v174 offset:32096
	ds_read_b128 v[70:73], v174 offset:32352
	ds_read_b128 v[74:77], v174 offset:32608
	ds_read_b128 v[78:81], v174 offset:32864
	ds_read_b128 v[82:85], v174 offset:33120
	ds_read_b128 v[86:89], v174 offset:33376
	ds_read_b128 v[90:93], v175 offset:34144
	ds_read_b32 v94, v163 offset:33632
	ds_read_b32 v95, v163 offset:33888
	v_pk_mul_f32 v[148:149], v[24:25], v[40:41] op_sel_hi:[1,0]
	v_pk_mul_f32 v[150:151], v[26:27], v[40:41] op_sel_hi:[1,0]
	v_add_f32_e32 v168, v96, v97
	v_add_f32_e32 v166, v98, v99
	v_add_f32_e32 v169, v100, v101
	v_add_f32_e32 v170, v172, v173
	v_pk_fma_f32 v[148:149], v[32:33], v[40:41], v[148:149] op_sel:[0,1,0] op_sel_hi:[1,1,1]
	v_pk_fma_f32 v[150:151], v[34:35], v[40:41], v[150:151] op_sel:[0,1,0] op_sel_hi:[1,1,1]
	v_add_f32_dpp v168, v168, v168 row_mirror row_mask:0xf bank_mask:0xf bound_ctrl:1
	v_add_f32_dpp v166, v166, v166 row_mirror row_mask:0xf bank_mask:0xf bound_ctrl:1
	v_add_f32_dpp v169, v169, v169 row_mirror row_mask:0xf bank_mask:0xf bound_ctrl:1
	v_add_f32_dpp v170, v170, v170 row_mirror row_mask:0xf bank_mask:0xf bound_ctrl:1
	v_add_f32_dpp v168, v168, v168 row_half_mirror row_mask:0xf bank_mask:0xf bound_ctrl:1
	v_add_f32_dpp v166, v166, v166 row_half_mirror row_mask:0xf bank_mask:0xf bound_ctrl:1
	v_add_f32_dpp v169, v169, v169 row_half_mirror row_mask:0xf bank_mask:0xf bound_ctrl:1
	v_add_f32_dpp v170, v170, v170 row_half_mirror row_mask:0xf bank_mask:0xf bound_ctrl:1
	v_add_f32_dpp v168, v168, v168 quad_perm:[1,0,3,2] row_mask:0xf bank_mask:0xf bound_ctrl:1
	v_add_f32_dpp v166, v166, v166 quad_perm:[1,0,3,2] row_mask:0xf bank_mask:0xf bound_ctrl:1
	v_add_f32_dpp v169, v169, v169 quad_perm:[1,0,3,2] row_mask:0xf bank_mask:0xf bound_ctrl:1
	v_add_f32_dpp v170, v170, v170 quad_perm:[1,0,3,2] row_mask:0xf bank_mask:0xf bound_ctrl:1
	v_add_f32_dpp v168, v168, v168 quad_perm:[2,3,0,1] row_mask:0xf bank_mask:0xf bound_ctrl:1
	v_add_f32_dpp v166, v166, v166 quad_perm:[2,3,0,1] row_mask:0xf bank_mask:0xf bound_ctrl:1
	v_add_f32_dpp v169, v169, v169 quad_perm:[2,3,0,1] row_mask:0xf bank_mask:0xf bound_ctrl:1
	v_add_f32_dpp v170, v170, v170 quad_perm:[2,3,0,1] row_mask:0xf bank_mask:0xf bound_ctrl:1
	v_fma_f32 v164, v40, v37, v169
	v_fma_f32 v171, v40, v39, v170
	v_pk_fma_f32 v[148:149], v[20:21], v[166:167], v[148:149] op_sel_hi:[1,0,1]
	v_fma_f32 v167, v166, v36, v164
	v_pk_fma_f32 v[150:151], v[22:23], v[166:167], v[150:151] op_sel_hi:[1,0,1]
	v_fma_f32 v171, v166, v38, v171
	v_cndmask_b32_e64 v162, v162, v168, s[52:53]
	v_pk_fma_f32 v[148:149], v[28:29], v[166:167], v[148:149] op_sel:[0,1,0] op_sel_hi:[1,1,1]
	v_pk_fma_f32 v[150:151], v[30:31], v[166:167], v[150:151] op_sel:[0,1,0] op_sel_hi:[1,1,1]
	v_cndmask_b32_e64 v162, v162, v171, s[54:55]
	v_pk_fma_f32 v[144:145], v[144:145], v[16:17], v[148:149]
	v_pk_fma_f32 v[146:147], v[146:147], v[18:19], v[150:151]
	s_waitcnt lgkmcnt(0)
	v_pk_mul_f32 v[96:97], v[144:145], v[12:13]
	v_pk_mul_f32 v[98:99], v[144:145], v[54:55]
	v_pk_mul_f32 v[100:101], v[144:145], v[58:59]
	v_pk_mul_f32 v[172:173], v[144:145], v[62:63]
	v_pk_fma_f32 v[96:97], v[146:147], v[14:15], v[96:97]
	v_pk_fma_f32 v[98:99], v[146:147], v[56:57], v[98:99]
	v_pk_fma_f32 v[100:101], v[146:147], v[60:61], v[100:101]
	v_pk_fma_f32 v[172:173], v[146:147], v[64:65], v[172:173]
	ds_read_b128 v[0:3], v174 offset:34176
	ds_read_b128 v[4:7], v174 offset:34432
	ds_read_b128 v[8:11], v174 offset:34688
	ds_read_b128 v[12:15], v174 offset:34944
	ds_read_b128 v[16:19], v174 offset:35200
	ds_read_b128 v[20:23], v174 offset:35456
	ds_read_b128 v[24:27], v174 offset:35712
	ds_read_b128 v[28:31], v174 offset:35968
	ds_read_b128 v[32:35], v174 offset:36224
	ds_read_b128 v[36:39], v175 offset:36992
	ds_read_b32 v40, v163 offset:36480
	ds_read_b32 v41, v163 offset:36736
	v_pk_mul_f32 v[148:149], v[78:79], v[94:95] op_sel_hi:[1,0]
	v_pk_mul_f32 v[150:151], v[80:81], v[94:95] op_sel_hi:[1,0]
	v_add_f32_e32 v168, v96, v97
	v_add_f32_e32 v166, v98, v99
	v_add_f32_e32 v169, v100, v101
	v_add_f32_e32 v170, v172, v173
	v_pk_fma_f32 v[148:149], v[86:87], v[94:95], v[148:149] op_sel:[0,1,0] op_sel_hi:[1,1,1]
	v_pk_fma_f32 v[150:151], v[88:89], v[94:95], v[150:151] op_sel:[0,1,0] op_sel_hi:[1,1,1]
	v_add_f32_dpp v168, v168, v168 row_mirror row_mask:0xf bank_mask:0xf bound_ctrl:1
	v_add_f32_dpp v166, v166, v166 row_mirror row_mask:0xf bank_mask:0xf bound_ctrl:1
	v_add_f32_dpp v169, v169, v169 row_mirror row_mask:0xf bank_mask:0xf bound_ctrl:1
	v_add_f32_dpp v170, v170, v170 row_mirror row_mask:0xf bank_mask:0xf bound_ctrl:1
	v_add_f32_dpp v168, v168, v168 row_half_mirror row_mask:0xf bank_mask:0xf bound_ctrl:1
	v_add_f32_dpp v166, v166, v166 row_half_mirror row_mask:0xf bank_mask:0xf bound_ctrl:1
	v_add_f32_dpp v169, v169, v169 row_half_mirror row_mask:0xf bank_mask:0xf bound_ctrl:1
	v_add_f32_dpp v170, v170, v170 row_half_mirror row_mask:0xf bank_mask:0xf bound_ctrl:1
	v_add_f32_dpp v168, v168, v168 quad_perm:[1,0,3,2] row_mask:0xf bank_mask:0xf bound_ctrl:1
	v_add_f32_dpp v166, v166, v166 quad_perm:[1,0,3,2] row_mask:0xf bank_mask:0xf bound_ctrl:1
	v_add_f32_dpp v169, v169, v169 quad_perm:[1,0,3,2] row_mask:0xf bank_mask:0xf bound_ctrl:1
	v_add_f32_dpp v170, v170, v170 quad_perm:[1,0,3,2] row_mask:0xf bank_mask:0xf bound_ctrl:1
	v_add_f32_dpp v168, v168, v168 quad_perm:[2,3,0,1] row_mask:0xf bank_mask:0xf bound_ctrl:1
	v_add_f32_dpp v166, v166, v166 quad_perm:[2,3,0,1] row_mask:0xf bank_mask:0xf bound_ctrl:1
	v_add_f32_dpp v169, v169, v169 quad_perm:[2,3,0,1] row_mask:0xf bank_mask:0xf bound_ctrl:1
	v_add_f32_dpp v170, v170, v170 quad_perm:[2,3,0,1] row_mask:0xf bank_mask:0xf bound_ctrl:1
	v_fma_f32 v164, v94, v91, v169
	v_fma_f32 v171, v94, v93, v170
	v_pk_fma_f32 v[148:149], v[74:75], v[166:167], v[148:149] op_sel_hi:[1,0,1]
	v_fma_f32 v167, v166, v90, v164
	v_pk_fma_f32 v[150:151], v[76:77], v[166:167], v[150:151] op_sel_hi:[1,0,1]
	v_fma_f32 v171, v166, v92, v171
	v_cndmask_b32_e64 v162, v162, v168, s[56:57]
	v_pk_fma_f32 v[148:149], v[82:83], v[166:167], v[148:149] op_sel:[0,1,0] op_sel_hi:[1,1,1]
	v_pk_fma_f32 v[150:151], v[84:85], v[166:167], v[150:151] op_sel:[0,1,0] op_sel_hi:[1,1,1]
	v_cndmask_b32_e64 v162, v162, v171, s[58:59]
	v_pk_fma_f32 v[144:145], v[144:145], v[70:71], v[148:149]
	v_pk_fma_f32 v[146:147], v[146:147], v[72:73], v[150:151]
	s_waitcnt lgkmcnt(0)
	v_pk_mul_f32 v[96:97], v[144:145], v[66:67]
	v_pk_mul_f32 v[98:99], v[144:145], v[0:1]
	v_pk_mul_f32 v[100:101], v[144:145], v[4:5]
	v_pk_mul_f32 v[172:173], v[144:145], v[8:9]
	v_pk_fma_f32 v[96:97], v[146:147], v[68:69], v[96:97]
	v_pk_fma_f32 v[98:99], v[146:147], v[2:3], v[98:99]
	v_pk_fma_f32 v[100:101], v[146:147], v[6:7], v[100:101]
	v_pk_fma_f32 v[172:173], v[146:147], v[10:11], v[172:173]
	ds_read_b128 v[54:57], v174 offset:37024
	ds_read_b128 v[58:61], v174 offset:37280
	ds_read_b128 v[62:65], v174 offset:37536
	ds_read_b128 v[66:69], v174 offset:37792
	ds_read_b128 v[70:73], v174 offset:38048
	ds_read_b128 v[74:77], v174 offset:38304
	ds_read_b128 v[78:81], v174 offset:38560
	ds_read_b128 v[82:85], v174 offset:38816
	ds_read_b128 v[86:89], v174 offset:39072
	ds_read_b128 v[90:93], v175 offset:39840
	ds_read_b32 v94, v163 offset:39328
	ds_read_b32 v95, v163 offset:39584
	v_pk_mul_f32 v[148:149], v[24:25], v[40:41] op_sel_hi:[1,0]
	v_pk_mul_f32 v[150:151], v[26:27], v[40:41] op_sel_hi:[1,0]
	v_add_f32_e32 v168, v96, v97
	v_add_f32_e32 v166, v98, v99
	v_add_f32_e32 v169, v100, v101
	v_add_f32_e32 v170, v172, v173
	v_pk_fma_f32 v[148:149], v[32:33], v[40:41], v[148:149] op_sel:[0,1,0] op_sel_hi:[1,1,1]
	v_pk_fma_f32 v[150:151], v[34:35], v[40:41], v[150:151] op_sel:[0,1,0] op_sel_hi:[1,1,1]
	v_add_f32_dpp v168, v168, v168 row_mirror row_mask:0xf bank_mask:0xf bound_ctrl:1
	v_add_f32_dpp v166, v166, v166 row_mirror row_mask:0xf bank_mask:0xf bound_ctrl:1
	v_add_f32_dpp v169, v169, v169 row_mirror row_mask:0xf bank_mask:0xf bound_ctrl:1
	v_add_f32_dpp v170, v170, v170 row_mirror row_mask:0xf bank_mask:0xf bound_ctrl:1
	v_add_f32_dpp v168, v168, v168 row_half_mirror row_mask:0xf bank_mask:0xf bound_ctrl:1
	v_add_f32_dpp v166, v166, v166 row_half_mirror row_mask:0xf bank_mask:0xf bound_ctrl:1
	v_add_f32_dpp v169, v169, v169 row_half_mirror row_mask:0xf bank_mask:0xf bound_ctrl:1
	v_add_f32_dpp v170, v170, v170 row_half_mirror row_mask:0xf bank_mask:0xf bound_ctrl:1
	v_add_f32_dpp v168, v168, v168 quad_perm:[1,0,3,2] row_mask:0xf bank_mask:0xf bound_ctrl:1
	v_add_f32_dpp v166, v166, v166 quad_perm:[1,0,3,2] row_mask:0xf bank_mask:0xf bound_ctrl:1
	v_add_f32_dpp v169, v169, v169 quad_perm:[1,0,3,2] row_mask:0xf bank_mask:0xf bound_ctrl:1
	v_add_f32_dpp v170, v170, v170 quad_perm:[1,0,3,2] row_mask:0xf bank_mask:0xf bound_ctrl:1
	v_add_f32_dpp v168, v168, v168 quad_perm:[2,3,0,1] row_mask:0xf bank_mask:0xf bound_ctrl:1
	v_add_f32_dpp v166, v166, v166 quad_perm:[2,3,0,1] row_mask:0xf bank_mask:0xf bound_ctrl:1
	v_add_f32_dpp v169, v169, v169 quad_perm:[2,3,0,1] row_mask:0xf bank_mask:0xf bound_ctrl:1
	v_add_f32_dpp v170, v170, v170 quad_perm:[2,3,0,1] row_mask:0xf bank_mask:0xf bound_ctrl:1
	v_fma_f32 v164, v40, v37, v169
	v_fma_f32 v171, v40, v39, v170
	v_pk_fma_f32 v[148:149], v[20:21], v[166:167], v[148:149] op_sel_hi:[1,0,1]
	v_fma_f32 v167, v166, v36, v164
	v_pk_fma_f32 v[150:151], v[22:23], v[166:167], v[150:151] op_sel_hi:[1,0,1]
	v_fma_f32 v171, v166, v38, v171
	v_cndmask_b32_e64 v162, v162, v168, s[60:61]
	v_pk_fma_f32 v[148:149], v[28:29], v[166:167], v[148:149] op_sel:[0,1,0] op_sel_hi:[1,1,1]
	v_pk_fma_f32 v[150:151], v[30:31], v[166:167], v[150:151] op_sel:[0,1,0] op_sel_hi:[1,1,1]
	v_cndmask_b32_e64 v162, v162, v171, s[62:63]
	v_pk_fma_f32 v[144:145], v[144:145], v[16:17], v[148:149]
	v_pk_fma_f32 v[146:147], v[146:147], v[18:19], v[150:151]
	s_waitcnt lgkmcnt(0)
	v_pk_mul_f32 v[96:97], v[144:145], v[12:13]
	v_pk_mul_f32 v[98:99], v[144:145], v[54:55]
	v_pk_mul_f32 v[100:101], v[144:145], v[58:59]
	v_pk_mul_f32 v[172:173], v[144:145], v[62:63]
	v_pk_fma_f32 v[96:97], v[146:147], v[14:15], v[96:97]
	v_pk_fma_f32 v[98:99], v[146:147], v[56:57], v[98:99]
	v_pk_fma_f32 v[100:101], v[146:147], v[60:61], v[100:101]
	v_pk_fma_f32 v[172:173], v[146:147], v[64:65], v[172:173]
	ds_read_b128 v[0:3], v174 offset:39872
	ds_read_b128 v[4:7], v174 offset:40128
	ds_read_b128 v[8:11], v174 offset:40384
	ds_read_b128 v[12:15], v174 offset:40640
	ds_read_b128 v[16:19], v174 offset:40896
	ds_read_b128 v[20:23], v174 offset:41152
	ds_read_b128 v[24:27], v174 offset:41408
	ds_read_b128 v[28:31], v174 offset:41664
	ds_read_b128 v[32:35], v174 offset:41920
	ds_read_b128 v[36:39], v175 offset:42688
	ds_read_b32 v40, v163 offset:42176
	ds_read_b32 v41, v163 offset:42432
	v_pk_mul_f32 v[148:149], v[78:79], v[94:95] op_sel_hi:[1,0]
	v_pk_mul_f32 v[150:151], v[80:81], v[94:95] op_sel_hi:[1,0]
	v_add_f32_e32 v168, v96, v97
	v_add_f32_e32 v166, v98, v99
	v_add_f32_e32 v169, v100, v101
	v_add_f32_e32 v170, v172, v173
	v_pk_fma_f32 v[148:149], v[86:87], v[94:95], v[148:149] op_sel:[0,1,0] op_sel_hi:[1,1,1]
	v_pk_fma_f32 v[150:151], v[88:89], v[94:95], v[150:151] op_sel:[0,1,0] op_sel_hi:[1,1,1]
	v_add_f32_dpp v168, v168, v168 row_mirror row_mask:0xf bank_mask:0xf bound_ctrl:1
	v_add_f32_dpp v166, v166, v166 row_mirror row_mask:0xf bank_mask:0xf bound_ctrl:1
	v_add_f32_dpp v169, v169, v169 row_mirror row_mask:0xf bank_mask:0xf bound_ctrl:1
	v_add_f32_dpp v170, v170, v170 row_mirror row_mask:0xf bank_mask:0xf bound_ctrl:1
	v_add_f32_dpp v168, v168, v168 row_half_mirror row_mask:0xf bank_mask:0xf bound_ctrl:1
	v_add_f32_dpp v166, v166, v166 row_half_mirror row_mask:0xf bank_mask:0xf bound_ctrl:1
	v_add_f32_dpp v169, v169, v169 row_half_mirror row_mask:0xf bank_mask:0xf bound_ctrl:1
	v_add_f32_dpp v170, v170, v170 row_half_mirror row_mask:0xf bank_mask:0xf bound_ctrl:1
	v_add_f32_dpp v168, v168, v168 quad_perm:[1,0,3,2] row_mask:0xf bank_mask:0xf bound_ctrl:1
	v_add_f32_dpp v166, v166, v166 quad_perm:[1,0,3,2] row_mask:0xf bank_mask:0xf bound_ctrl:1
	v_add_f32_dpp v169, v169, v169 quad_perm:[1,0,3,2] row_mask:0xf bank_mask:0xf bound_ctrl:1
	v_add_f32_dpp v170, v170, v170 quad_perm:[1,0,3,2] row_mask:0xf bank_mask:0xf bound_ctrl:1
	v_add_f32_dpp v168, v168, v168 quad_perm:[2,3,0,1] row_mask:0xf bank_mask:0xf bound_ctrl:1
	v_add_f32_dpp v166, v166, v166 quad_perm:[2,3,0,1] row_mask:0xf bank_mask:0xf bound_ctrl:1
	v_add_f32_dpp v169, v169, v169 quad_perm:[2,3,0,1] row_mask:0xf bank_mask:0xf bound_ctrl:1
	v_add_f32_dpp v170, v170, v170 quad_perm:[2,3,0,1] row_mask:0xf bank_mask:0xf bound_ctrl:1
	v_fma_f32 v164, v94, v91, v169
	v_fma_f32 v171, v94, v93, v170
	v_pk_fma_f32 v[148:149], v[74:75], v[166:167], v[148:149] op_sel_hi:[1,0,1]
	v_fma_f32 v167, v166, v90, v164
	v_pk_fma_f32 v[150:151], v[76:77], v[166:167], v[150:151] op_sel_hi:[1,0,1]
	v_fma_f32 v171, v166, v92, v171
	v_cndmask_b32_e64 v162, v162, v168, s[64:65]
	v_pk_fma_f32 v[148:149], v[82:83], v[166:167], v[148:149] op_sel:[0,1,0] op_sel_hi:[1,1,1]
	v_pk_fma_f32 v[150:151], v[84:85], v[166:167], v[150:151] op_sel:[0,1,0] op_sel_hi:[1,1,1]
	v_cndmask_b32_e64 v162, v162, v171, s[66:67]
	v_pk_fma_f32 v[144:145], v[144:145], v[70:71], v[148:149]
	v_pk_fma_f32 v[146:147], v[146:147], v[72:73], v[150:151]
	s_waitcnt lgkmcnt(0)
	v_pk_mul_f32 v[96:97], v[144:145], v[66:67]
	v_pk_mul_f32 v[98:99], v[144:145], v[0:1]
	v_pk_mul_f32 v[100:101], v[144:145], v[4:5]
	v_pk_mul_f32 v[172:173], v[144:145], v[8:9]
	v_pk_fma_f32 v[96:97], v[146:147], v[68:69], v[96:97]
	v_pk_fma_f32 v[98:99], v[146:147], v[2:3], v[98:99]
	v_pk_fma_f32 v[100:101], v[146:147], v[6:7], v[100:101]
	v_pk_fma_f32 v[172:173], v[146:147], v[10:11], v[172:173]
	ds_read_b128 v[54:57], v174 offset:42720
	ds_read_b128 v[58:61], v174 offset:42976
	ds_read_b128 v[62:65], v174 offset:43232
	ds_read_b128 v[66:69], v174 offset:43488
	ds_read_b128 v[70:73], v174 offset:43744
	ds_read_b128 v[74:77], v174 offset:44000
	ds_read_b128 v[78:81], v174 offset:44256
	ds_read_b128 v[82:85], v174 offset:44512
	ds_read_b128 v[86:89], v174 offset:44768
	ds_read_b128 v[90:93], v175 offset:45536
	ds_read_b32 v94, v163 offset:45024
	ds_read_b32 v95, v163 offset:45280
	v_pk_mul_f32 v[148:149], v[24:25], v[40:41] op_sel_hi:[1,0]
	v_pk_mul_f32 v[150:151], v[26:27], v[40:41] op_sel_hi:[1,0]
	v_add_f32_e32 v168, v96, v97
	v_add_f32_e32 v166, v98, v99
	v_add_f32_e32 v169, v100, v101
	v_add_f32_e32 v170, v172, v173
	v_pk_fma_f32 v[148:149], v[32:33], v[40:41], v[148:149] op_sel:[0,1,0] op_sel_hi:[1,1,1]
	v_pk_fma_f32 v[150:151], v[34:35], v[40:41], v[150:151] op_sel:[0,1,0] op_sel_hi:[1,1,1]
	v_add_f32_dpp v168, v168, v168 row_mirror row_mask:0xf bank_mask:0xf bound_ctrl:1
	v_add_f32_dpp v166, v166, v166 row_mirror row_mask:0xf bank_mask:0xf bound_ctrl:1
	v_add_f32_dpp v169, v169, v169 row_mirror row_mask:0xf bank_mask:0xf bound_ctrl:1
	v_add_f32_dpp v170, v170, v170 row_mirror row_mask:0xf bank_mask:0xf bound_ctrl:1
	v_add_f32_dpp v168, v168, v168 row_half_mirror row_mask:0xf bank_mask:0xf bound_ctrl:1
	v_add_f32_dpp v166, v166, v166 row_half_mirror row_mask:0xf bank_mask:0xf bound_ctrl:1
	v_add_f32_dpp v169, v169, v169 row_half_mirror row_mask:0xf bank_mask:0xf bound_ctrl:1
	v_add_f32_dpp v170, v170, v170 row_half_mirror row_mask:0xf bank_mask:0xf bound_ctrl:1
	v_add_f32_dpp v168, v168, v168 quad_perm:[1,0,3,2] row_mask:0xf bank_mask:0xf bound_ctrl:1
	v_add_f32_dpp v166, v166, v166 quad_perm:[1,0,3,2] row_mask:0xf bank_mask:0xf bound_ctrl:1
	v_add_f32_dpp v169, v169, v169 quad_perm:[1,0,3,2] row_mask:0xf bank_mask:0xf bound_ctrl:1
	v_add_f32_dpp v170, v170, v170 quad_perm:[1,0,3,2] row_mask:0xf bank_mask:0xf bound_ctrl:1
	v_add_f32_dpp v168, v168, v168 quad_perm:[2,3,0,1] row_mask:0xf bank_mask:0xf bound_ctrl:1
	v_add_f32_dpp v166, v166, v166 quad_perm:[2,3,0,1] row_mask:0xf bank_mask:0xf bound_ctrl:1
	v_add_f32_dpp v169, v169, v169 quad_perm:[2,3,0,1] row_mask:0xf bank_mask:0xf bound_ctrl:1
	v_add_f32_dpp v170, v170, v170 quad_perm:[2,3,0,1] row_mask:0xf bank_mask:0xf bound_ctrl:1
	v_fma_f32 v164, v40, v37, v169
	v_fma_f32 v171, v40, v39, v170
	v_pk_fma_f32 v[148:149], v[20:21], v[166:167], v[148:149] op_sel_hi:[1,0,1]
	v_fma_f32 v167, v166, v36, v164
	v_pk_fma_f32 v[150:151], v[22:23], v[166:167], v[150:151] op_sel_hi:[1,0,1]
	v_fma_f32 v171, v166, v38, v171
	v_cndmask_b32_e64 v162, v162, v168, s[68:69]
	v_pk_fma_f32 v[148:149], v[28:29], v[166:167], v[148:149] op_sel:[0,1,0] op_sel_hi:[1,1,1]
	v_pk_fma_f32 v[150:151], v[30:31], v[166:167], v[150:151] op_sel:[0,1,0] op_sel_hi:[1,1,1]
	v_cndmask_b32_e64 v162, v162, v171, s[70:71]
	v_pk_fma_f32 v[144:145], v[144:145], v[16:17], v[148:149]
	v_pk_fma_f32 v[146:147], v[146:147], v[18:19], v[150:151]
	s_waitcnt lgkmcnt(0)
	v_pk_mul_f32 v[96:97], v[144:145], v[12:13]
	v_pk_mul_f32 v[98:99], v[144:145], v[54:55]
	v_pk_mul_f32 v[100:101], v[144:145], v[58:59]
	v_pk_mul_f32 v[172:173], v[144:145], v[62:63]
	v_pk_fma_f32 v[96:97], v[146:147], v[14:15], v[96:97]
	v_pk_fma_f32 v[98:99], v[146:147], v[56:57], v[98:99]
	v_pk_fma_f32 v[100:101], v[146:147], v[60:61], v[100:101]
	v_pk_fma_f32 v[172:173], v[146:147], v[64:65], v[172:173]
	v_pk_mul_f32 v[148:149], v[78:79], v[94:95] op_sel_hi:[1,0]
	v_pk_mul_f32 v[150:151], v[80:81], v[94:95] op_sel_hi:[1,0]
	v_add_f32_e32 v168, v96, v97
	v_add_f32_e32 v166, v98, v99
	v_add_f32_e32 v169, v100, v101
	v_add_f32_e32 v170, v172, v173
	v_pk_fma_f32 v[148:149], v[86:87], v[94:95], v[148:149] op_sel:[0,1,0] op_sel_hi:[1,1,1]
	v_pk_fma_f32 v[150:151], v[88:89], v[94:95], v[150:151] op_sel:[0,1,0] op_sel_hi:[1,1,1]
	v_add_f32_dpp v168, v168, v168 row_mirror row_mask:0xf bank_mask:0xf bound_ctrl:1
	v_add_f32_dpp v166, v166, v166 row_mirror row_mask:0xf bank_mask:0xf bound_ctrl:1
	v_add_f32_dpp v169, v169, v169 row_mirror row_mask:0xf bank_mask:0xf bound_ctrl:1
	v_add_f32_dpp v170, v170, v170 row_mirror row_mask:0xf bank_mask:0xf bound_ctrl:1
	v_add_f32_dpp v168, v168, v168 row_half_mirror row_mask:0xf bank_mask:0xf bound_ctrl:1
	v_add_f32_dpp v166, v166, v166 row_half_mirror row_mask:0xf bank_mask:0xf bound_ctrl:1
	v_add_f32_dpp v169, v169, v169 row_half_mirror row_mask:0xf bank_mask:0xf bound_ctrl:1
	v_add_f32_dpp v170, v170, v170 row_half_mirror row_mask:0xf bank_mask:0xf bound_ctrl:1
	v_add_f32_dpp v168, v168, v168 quad_perm:[1,0,3,2] row_mask:0xf bank_mask:0xf bound_ctrl:1
	v_add_f32_dpp v166, v166, v166 quad_perm:[1,0,3,2] row_mask:0xf bank_mask:0xf bound_ctrl:1
	v_add_f32_dpp v169, v169, v169 quad_perm:[1,0,3,2] row_mask:0xf bank_mask:0xf bound_ctrl:1
	v_add_f32_dpp v170, v170, v170 quad_perm:[1,0,3,2] row_mask:0xf bank_mask:0xf bound_ctrl:1
	v_add_f32_dpp v168, v168, v168 quad_perm:[2,3,0,1] row_mask:0xf bank_mask:0xf bound_ctrl:1
	v_add_f32_dpp v166, v166, v166 quad_perm:[2,3,0,1] row_mask:0xf bank_mask:0xf bound_ctrl:1
	v_add_f32_dpp v169, v169, v169 quad_perm:[2,3,0,1] row_mask:0xf bank_mask:0xf bound_ctrl:1
	v_add_f32_dpp v170, v170, v170 quad_perm:[2,3,0,1] row_mask:0xf bank_mask:0xf bound_ctrl:1
	v_fma_f32 v164, v94, v91, v169
	v_fma_f32 v171, v94, v93, v170
	v_pk_fma_f32 v[148:149], v[74:75], v[166:167], v[148:149] op_sel_hi:[1,0,1]
	v_fma_f32 v167, v166, v90, v164
	v_pk_fma_f32 v[150:151], v[76:77], v[166:167], v[150:151] op_sel_hi:[1,0,1]
	v_fma_f32 v171, v166, v92, v171
	v_cndmask_b32_e64 v162, v162, v168, s[44:45]
	v_pk_fma_f32 v[148:149], v[82:83], v[166:167], v[148:149] op_sel:[0,1,0] op_sel_hi:[1,1,1]
	v_pk_fma_f32 v[150:151], v[84:85], v[166:167], v[150:151] op_sel:[0,1,0] op_sel_hi:[1,1,1]
	v_cndmask_b32_e64 v162, v162, v171, s[42:43]
	v_pk_fma_f32 v[144:145], v[144:145], v[70:71], v[148:149]
	v_pk_fma_f32 v[146:147], v[146:147], v[72:73], v[150:151]
	v_mov_b64_e32 v[24:25], v[66:67]
	v_mov_b64_e32 v[26:27], v[68:69]
	s_mov_b64 s[92:93], 0
